# baseline (speedup 1.0000x reference)
; __device__ __forceinline__ unsigned cvt_pk(float lo, float hi) { unsigned r; asm("v_cvt_pk_bf16_f32 %0, %1, %2" : "=v"(r) : "v"(lo), "v"(hi)); return r; }
; __device__ __forceinline__ void sp_load(const Params& p, int item, int tid, u32x2 (&wreg)[8], unsigned (&vreg)[32]) {
;     ...
;     const float* wsp = p.in[15] + (size_t)g * 16384;
; #pragma unroll
;     for (int ii = 0; ii < 8; ++ii) { const int pc = tid + 512 * ii, t = pc >> 5, s4 = (pc & 31) * 4; const f32x4 wv = *(const f32x4*)(wsp + t * 128 + s4); float x[4];
; #pragma unroll
;         for (int j = 0; j < 4; ++j) x[j] = (s4 + j <= t && t < L) ? wv[j] : 0.f;
;         wreg[ii].x = cvt_pk(x[0], x[1]); wreg[ii].y = cvt_pk(x[2], x[3]); }
.LBB0_1445:
	v_readlane_b32 s60, v251, 34
	v_readlane_b32 s61, v251, 35
	v_readlane_b32 s62, v251, 36
	v_readlane_b32 s63, v251, 37
	v_readlane_b32 s64, v251, 38
	v_readlane_b32 s65, v251, 39
	v_readlane_b32 s66, v251, 40
	v_readlane_b32 s67, v251, 41
	v_readlane_b32 s68, v251, 42
	v_readlane_b32 s69, v251, 43
	s_and_b32 s19, s58, 7
	v_readlane_b32 s70, v251, 44
	v_readlane_b32 s71, v251, 45
	v_readlane_b32 s72, v251, 46
	v_readlane_b32 s73, v251, 47
	v_readlane_b32 s74, v251, 48
	v_readlane_b32 s75, v251, 49
	s_mov_b64 s[60:61], s[68:69]
	s_lshl_b32 s2, s19, 16
	s_mov_b64 s[66:67], s[74:75]
	v_lshlrev_b32_e32 v0, 2, v111
	s_add_u32 s2, s66, s2
	s_waitcnt vmcnt(0)
	v_and_b32_e32 v6, 0x7c, v0
	v_ashrrev_i32_e32 v12, 5, v111
	s_addc_u32 s3, s67, 0
	v_lshlrev_b32_e32 v0, 2, v6
	v_lshlrev_b32_e32 v4, 7, v12
	v_lshl_add_u64 v[2:3], s[2:3], 0, v[0:1]
	v_ashrrev_i32_e32 v5, 31, v4
	v_lshl_add_u64 v[4:5], v[4:5], 2, v[2:3]
	global_load_dwordx4 v[8:11], v[4:5], off
	v_cmp_gt_i32_e32 vcc, s18, v12
	v_cmp_le_i32_e64 s[2:3], v6, v12
	s_and_b64 s[2:3], s[2:3], vcc
	v_or_b32_e32 v0, 2, v6
	v_or_b32_e32 v7, 3, v6
	s_mov_b64 s[62:63], s[70:71]
	s_mov_b64 s[64:65], s[72:73]
	s_waitcnt vmcnt(0)
	v_cndmask_b32_e64 v4, 0, v8, s[2:3]
	v_cmp_lt_i32_e64 s[2:3], v6, v12
	s_and_b64 s[2:3], s[2:3], vcc
	s_nop 0
	v_cndmask_b32_e64 v5, 0, v9, s[2:3]
	v_cmp_le_i32_e64 s[2:3], v0, v12
	s_and_b64 s[2:3], s[2:3], vcc
	v_cvt_pk_bf16_f32 v94, v4, v5
	v_add_u32_e32 v4, 0x200, v111
	v_cndmask_b32_e64 v8, 0, v10, s[2:3]
	v_cmp_le_i32_e64 s[2:3], v7, v12
	v_ashrrev_i32_e32 v12, 5, v4
	v_lshlrev_b32_e32 v4, 7, v12
	s_and_b64 vcc, s[2:3], vcc
	v_ashrrev_i32_e32 v5, 31, v4
	v_cndmask_b32_e32 v9, 0, v11, vcc
	v_lshl_add_u64 v[4:5], v[4:5], 2, v[2:3]
	v_cvt_pk_bf16_f32 v95, v8, v9
	global_load_dwordx4 v[8:11], v[4:5], off
	v_cmp_gt_i32_e32 vcc, s18, v12
	v_cmp_le_i32_e64 s[2:3], v6, v12
	s_and_b64 s[2:3], s[2:3], vcc
	s_waitcnt vmcnt(0)
	v_cndmask_b32_e64 v4, 0, v8, s[2:3]
	v_cmp_lt_i32_e64 s[2:3], v6, v12
	s_and_b64 s[2:3], s[2:3], vcc
	s_nop 0
	v_cndmask_b32_e64 v5, 0, v9, s[2:3]
	v_cmp_le_i32_e64 s[2:3], v0, v12
	s_and_b64 s[2:3], s[2:3], vcc
	v_cvt_pk_bf16_f32 v96, v4, v5
	v_add_u32_e32 v4, 0x400, v111
	v_cndmask_b32_e64 v8, 0, v10, s[2:3]
	v_cmp_le_i32_e64 s[2:3], v7, v12
	v_ashrrev_i32_e32 v12, 5, v4
	v_lshlrev_b32_e32 v4, 7, v12
	s_and_b64 vcc, s[2:3], vcc
	v_ashrrev_i32_e32 v5, 31, v4
	v_cndmask_b32_e32 v9, 0, v11, vcc
	v_lshl_add_u64 v[4:5], v[4:5], 2, v[2:3]
	v_cvt_pk_bf16_f32 v97, v8, v9
	global_load_dwordx4 v[8:11], v[4:5], off
	v_cmp_gt_i32_e32 vcc, s18, v12
	v_cmp_le_i32_e64 s[2:3], v6, v12
	s_and_b64 s[2:3], s[2:3], vcc
	s_waitcnt vmcnt(0)
	v_cndmask_b32_e64 v4, 0, v8, s[2:3]
	v_cmp_lt_i32_e64 s[2:3], v6, v12
	s_and_b64 s[2:3], s[2:3], vcc
	s_nop 0
	v_cndmask_b32_e64 v5, 0, v9, s[2:3]
	v_cmp_le_i32_e64 s[2:3], v0, v12
	s_and_b64 s[2:3], s[2:3], vcc
	v_cvt_pk_bf16_f32 v98, v4, v5
	v_add_u32_e32 v4, 0x600, v111
	v_cndmask_b32_e64 v8, 0, v10, s[2:3]
	v_cmp_le_i32_e64 s[2:3], v7, v12
	v_ashrrev_i32_e32 v12, 5, v4
	v_lshlrev_b32_e32 v4, 7, v12
	s_and_b64 vcc, s[2:3], vcc
	v_ashrrev_i32_e32 v5, 31, v4
	v_cndmask_b32_e32 v9, 0, v11, vcc
	v_lshl_add_u64 v[4:5], v[4:5], 2, v[2:3]
	v_cvt_pk_bf16_f32 v99, v8, v9
	global_load_dwordx4 v[8:11], v[4:5], off
	v_cmp_gt_i32_e32 vcc, s18, v12
	v_cmp_le_i32_e64 s[2:3], v6, v12
	s_and_b64 s[2:3], s[2:3], vcc
	s_waitcnt vmcnt(0)
	v_cndmask_b32_e64 v4, 0, v8, s[2:3]
	v_cmp_lt_i32_e64 s[2:3], v6, v12
	s_and_b64 s[2:3], s[2:3], vcc
	s_nop 0
	v_cndmask_b32_e64 v5, 0, v9, s[2:3]
	v_cmp_le_i32_e64 s[2:3], v0, v12
	s_and_b64 s[2:3], s[2:3], vcc
	v_cvt_pk_bf16_f32 v100, v4, v5
	v_add_u32_e32 v4, 0x800, v111
	v_cndmask_b32_e64 v8, 0, v10, s[2:3]
	v_cmp_le_i32_e64 s[2:3], v7, v12
	v_ashrrev_i32_e32 v12, 5, v4
	v_lshlrev_b32_e32 v4, 7, v12
	s_and_b64 vcc, s[2:3], vcc
	v_ashrrev_i32_e32 v5, 31, v4
	v_cndmask_b32_e32 v9, 0, v11, vcc
	v_lshl_add_u64 v[4:5], v[4:5], 2, v[2:3]
	v_cvt_pk_bf16_f32 v101, v8, v9
	global_load_dwordx4 v[8:11], v[4:5], off
	v_cmp_gt_i32_e32 vcc, s18, v12
	v_cmp_le_i32_e64 s[2:3], v6, v12
	s_and_b64 s[2:3], s[2:3], vcc
	s_waitcnt vmcnt(0)
; __device__ __forceinline__ unsigned cvt_pk(float lo, float hi) { unsigned r; asm("v_cvt_pk_bf16_f32 %0, %1, %2" : "=v"(r) : "v"(lo), "v"(hi)); return r; }
; __device__ __forceinline__ int uni(int x) { return __builtin_amdgcn_readfirstlane(x); }
; __device__ __forceinline__ void sp_load(const Params& p, int item, int tid, u32x2 (&wreg)[8], unsigned (&vreg)[32]) {
;     ...
;     for (int ii = 0; ii < 8; ++ii) { const int pc = tid + 512 * ii, t = pc >> 5, s4 = (pc & 31) * 4; const f32x4 wv = *(const f32x4*)(wsp + t * 128 + s4); float x[4];
; #pragma unroll
;         for (int j = 0; j < 4; ++j) x[j] = (s4 + j <= t && t < L) ? wv[j] : 0.f;
;         wreg[ii].x = cvt_pk(x[0], x[1]); wreg[ii].y = cvt_pk(x[2], x[3]); }
;     const int ch = tid & 255, sh = uni(tid >> 8);
;     const bf16_t* vp = VLN + (size_t)(row0 + sh * 64) * D + g * 256;
; #pragma unroll
;     for (int q = 0; q < 32; ++q) { const int s = sh * 64 + 2 * q; unsigned lo = 0u, hi = 0u;
;         if (s < L) { lo = vp[(2 * q) * D + ch]; hi = vp[(2 * q + 1) * D + ch]; }
;         vreg[q] = lo | (hi << 16);
	v_cndmask_b32_e64 v4, 0, v8, s[2:3]
	v_cmp_lt_i32_e64 s[2:3], v6, v12
	s_and_b64 s[2:3], s[2:3], vcc
	s_nop 0
	v_cndmask_b32_e64 v5, 0, v9, s[2:3]
	v_cmp_le_i32_e64 s[2:3], v0, v12
	s_and_b64 s[2:3], s[2:3], vcc
	v_cvt_pk_bf16_f32 v102, v4, v5
	v_add_u32_e32 v4, 0xa00, v111
	v_cndmask_b32_e64 v8, 0, v10, s[2:3]
	v_cmp_le_i32_e64 s[2:3], v7, v12
	v_ashrrev_i32_e32 v12, 5, v4
	v_lshlrev_b32_e32 v4, 7, v12
	s_and_b64 vcc, s[2:3], vcc
	v_ashrrev_i32_e32 v5, 31, v4
	v_cndmask_b32_e32 v9, 0, v11, vcc
	v_lshl_add_u64 v[4:5], v[4:5], 2, v[2:3]
	v_cvt_pk_bf16_f32 v103, v8, v9
	global_load_dwordx4 v[8:11], v[4:5], off
	v_cmp_gt_i32_e32 vcc, s18, v12
	v_cmp_le_i32_e64 s[2:3], v6, v12
	s_and_b64 s[2:3], s[2:3], vcc
	s_waitcnt vmcnt(0)
	v_cndmask_b32_e64 v4, 0, v8, s[2:3]
	v_cmp_lt_i32_e64 s[2:3], v6, v12
	s_and_b64 s[2:3], s[2:3], vcc
	s_nop 0
	v_cndmask_b32_e64 v5, 0, v9, s[2:3]
	v_cmp_le_i32_e64 s[2:3], v0, v12
	s_and_b64 s[2:3], s[2:3], vcc
	v_cvt_pk_bf16_f32 v104, v4, v5
	v_add_u32_e32 v4, 0xc00, v111
	v_cndmask_b32_e64 v8, 0, v10, s[2:3]
	v_cmp_le_i32_e64 s[2:3], v7, v12
	v_ashrrev_i32_e32 v12, 5, v4
	v_lshlrev_b32_e32 v4, 7, v12
	s_and_b64 vcc, s[2:3], vcc
	v_ashrrev_i32_e32 v5, 31, v4
	v_cndmask_b32_e32 v9, 0, v11, vcc
	v_lshl_add_u64 v[4:5], v[4:5], 2, v[2:3]
	v_cvt_pk_bf16_f32 v105, v8, v9
	global_load_dwordx4 v[8:11], v[4:5], off
	v_cmp_gt_i32_e32 vcc, s18, v12
	v_cmp_le_i32_e64 s[2:3], v6, v12
	s_and_b64 s[2:3], s[2:3], vcc
	s_waitcnt vmcnt(0)
	v_cndmask_b32_e64 v4, 0, v8, s[2:3]
	v_cmp_lt_i32_e64 s[2:3], v6, v12
	s_and_b64 s[2:3], s[2:3], vcc
	s_nop 0
	v_cndmask_b32_e64 v5, 0, v9, s[2:3]
	v_cmp_le_i32_e64 s[2:3], v0, v12
	s_and_b64 s[2:3], s[2:3], vcc
	v_cvt_pk_bf16_f32 v106, v4, v5
	v_add_u32_e32 v4, 0xe00, v111
	v_cndmask_b32_e64 v8, 0, v10, s[2:3]
	v_cmp_le_i32_e64 s[2:3], v7, v12
	s_and_b64 vcc, s[2:3], vcc
	v_cndmask_b32_e32 v9, 0, v11, vcc
	v_cvt_pk_bf16_f32 v107, v8, v9
	v_ashrrev_i32_e32 v8, 5, v4
	v_lshlrev_b32_e32 v4, 7, v8
	v_ashrrev_i32_e32 v5, 31, v4
	v_lshl_add_u64 v[2:3], v[4:5], 2, v[2:3]
	global_load_dwordx4 v[2:5], v[2:3], off
	v_cmp_gt_i32_e32 vcc, s18, v8
	v_cmp_le_i32_e64 s[2:3], v6, v8
	s_and_b64 s[2:3], s[2:3], vcc
	s_waitcnt vmcnt(0)
	v_cndmask_b32_e64 v2, 0, v2, s[2:3]
	v_cmp_lt_i32_e64 s[2:3], v6, v8
	s_and_b64 s[2:3], s[2:3], vcc
	s_nop 0
	v_cndmask_b32_e64 v3, 0, v3, s[2:3]
	v_cmp_le_i32_e64 s[2:3], v0, v8
	s_and_b64 s[2:3], s[2:3], vcc
	v_cvt_pk_bf16_f32 v108, v2, v3
	v_mov_b32_e32 v3, 0
	v_cndmask_b32_e64 v0, 0, v4, s[2:3]
	v_cmp_le_i32_e64 s[2:3], v7, v8
	s_and_b64 vcc, s[2:3], vcc
	v_readfirstlane_b32 s2, v111
	s_ashr_i32 s2, s2, 2
	s_and_b32 s20, s2, 0xffffffc0
	s_add_i32 s2, s20, s17
	s_ashr_i32 s3, s2, 31
	s_lshl_b64 s[2:3], s[2:3], 12
	s_add_u32 s2, s92, s2
	v_readlane_b32 s17, v252, 27
	s_addc_u32 s3, s17, s3
	s_lshl_b32 s17, s19, 9
	s_add_u32 s2, s2, s17
	v_cndmask_b32_e32 v4, 0, v5, vcc
	v_cvt_pk_bf16_f32 v109, v0, v4
	s_addc_u32 s3, s3, 0
	s_sub_i32 s17, s18, s20
	v_mov_b32_e32 v0, 1
	s_cmp_lt_i32 s17, 1
	v_lshlrev_b32_sdwa v0, v0, v111 dst_sel:DWORD dst_unused:UNUSED_PAD src0_sel:DWORD src1_sel:BYTE_0
	v_mov_b32_e32 v2, 0
	s_cmp_gt_i32 s17, 63
	s_cbranch_scc1 .Lmy_sp1_fast
	s_cmp_lt_i32 s17, 1
	s_cbranch_scc1 .LBB0_1447
	v_lshl_add_u64 v[4:5], s[2:3], 0, v[0:1]
	v_add_co_u32_e32 v4, vcc, 0x1000, v4
	s_nop 1
	v_addc_co_u32_e32 v5, vcc, 0, v5, vcc
	global_load_ushort v2, v0, s[2:3]
	s_nop 0
	global_load_ushort v4, v[4:5], off
	s_waitcnt vmcnt(0)
	v_lshl_or_b32 v2, v4, 16, v2

; __device__ __forceinline__ int uni(int x) { return __builtin_amdgcn_readfirstlane(x); }
; __device__ __forceinline__ void sp_load(const Params& p, int item, int tid, u32x2 (&wreg)[8], unsigned (&vreg)[32]) {
;     ...
;     const int ch = tid & 255, sh = uni(tid >> 8);
;     const bf16_t* vp = VLN + (size_t)(row0 + sh * 64) * D + g * 256;
; #pragma unroll
;     for (int q = 0; q < 32; ++q) { const int s = sh * 64 + 2 * q; unsigned lo = 0u, hi = 0u;
;         if (s < L) { lo = vp[(2 * q) * D + ch]; hi = vp[(2 * q + 1) * D + ch]; }
;         vreg[q] = lo | (hi << 16);
;         if ((q & 7) == 7) asm volatile("" ::: "memory"); }
.Lmy_sp1_fast:
	s_mov_b32 s98, s2
	s_mov_b32 s99, s3
	s_add_u32 s98, s98, 0x1000
	s_addc_u32 s99, s99, 0
	global_load_ushort v2, v0, s[98:99] offset:-4096
	global_load_ushort v214, v0, s[98:99]
	s_add_u32 s98, s98, 0x2000
	s_addc_u32 s99, s99, 0
	global_load_ushort v3, v0, s[98:99] offset:-4096
	global_load_ushort v215, v0, s[98:99]
	s_add_u32 s98, s98, 0x2000
	s_addc_u32 s99, s99, 0
	global_load_ushort v4, v0, s[98:99] offset:-4096
	global_load_ushort v216, v0, s[98:99]
	s_add_u32 s98, s98, 0x2000
	s_addc_u32 s99, s99, 0
	global_load_ushort v5, v0, s[98:99] offset:-4096
	global_load_ushort v217, v0, s[98:99]
	s_add_u32 s98, s98, 0x2000
	s_addc_u32 s99, s99, 0
	global_load_ushort v6, v0, s[98:99] offset:-4096
	global_load_ushort v218, v0, s[98:99]
	s_add_u32 s98, s98, 0x2000
	s_addc_u32 s99, s99, 0
	global_load_ushort v7, v0, s[98:99] offset:-4096
	global_load_ushort v219, v0, s[98:99]
	s_add_u32 s98, s98, 0x2000
	s_addc_u32 s99, s99, 0
	global_load_ushort v8, v0, s[98:99] offset:-4096
	global_load_ushort v220, v0, s[98:99]
	s_add_u32 s98, s98, 0x2000
	s_addc_u32 s99, s99, 0
	global_load_ushort v9, v0, s[98:99] offset:-4096
	global_load_ushort v221, v0, s[98:99]
	s_add_u32 s98, s98, 0x2000
	s_addc_u32 s99, s99, 0
	global_load_ushort v10, v0, s[98:99] offset:-4096
	global_load_ushort v222, v0, s[98:99]
	s_add_u32 s98, s98, 0x2000
	s_addc_u32 s99, s99, 0
	global_load_ushort v11, v0, s[98:99] offset:-4096
	global_load_ushort v223, v0, s[98:99]
	s_add_u32 s98, s98, 0x2000
	s_addc_u32 s99, s99, 0
	global_load_ushort v12, v0, s[98:99] offset:-4096
	global_load_ushort v224, v0, s[98:99]
	s_add_u32 s98, s98, 0x2000
	s_addc_u32 s99, s99, 0
	global_load_ushort v13, v0, s[98:99] offset:-4096
	global_load_ushort v225, v0, s[98:99]
	s_add_u32 s98, s98, 0x2000
	s_addc_u32 s99, s99, 0
	global_load_ushort v14, v0, s[98:99] offset:-4096
	global_load_ushort v226, v0, s[98:99]
	s_add_u32 s98, s98, 0x2000
	s_addc_u32 s99, s99, 0
	global_load_ushort v15, v0, s[98:99] offset:-4096
	global_load_ushort v227, v0, s[98:99]
	s_add_u32 s98, s98, 0x2000
	s_addc_u32 s99, s99, 0
	global_load_ushort v16, v0, s[98:99] offset:-4096
	global_load_ushort v228, v0, s[98:99]
	s_add_u32 s98, s98, 0x2000
	s_addc_u32 s99, s99, 0
	global_load_ushort v17, v0, s[98:99] offset:-4096
	global_load_ushort v229, v0, s[98:99]
	s_add_u32 s98, s98, 0x2000
	s_addc_u32 s99, s99, 0
	global_load_ushort v18, v0, s[98:99] offset:-4096
	global_load_ushort v230, v0, s[98:99]
	s_add_u32 s98, s98, 0x2000
	s_addc_u32 s99, s99, 0
	global_load_ushort v19, v0, s[98:99] offset:-4096
	global_load_ushort v231, v0, s[98:99]
	s_add_u32 s98, s98, 0x2000
	s_addc_u32 s99, s99, 0
	global_load_ushort v20, v0, s[98:99] offset:-4096
	global_load_ushort v232, v0, s[98:99]
	s_add_u32 s98, s98, 0x2000
	s_addc_u32 s99, s99, 0
	global_load_ushort v21, v0, s[98:99] offset:-4096
	global_load_ushort v233, v0, s[98:99]
	s_add_u32 s98, s98, 0x2000
	s_addc_u32 s99, s99, 0
	global_load_ushort v22, v0, s[98:99] offset:-4096
	global_load_ushort v234, v0, s[98:99]
	s_add_u32 s98, s98, 0x2000
	s_addc_u32 s99, s99, 0
	global_load_ushort v23, v0, s[98:99] offset:-4096
	global_load_ushort v235, v0, s[98:99]
	s_add_u32 s98, s98, 0x2000
	s_addc_u32 s99, s99, 0
	global_load_ushort v24, v0, s[98:99] offset:-4096
	global_load_ushort v236, v0, s[98:99]
	s_add_u32 s98, s98, 0x2000
	s_addc_u32 s99, s99, 0
	global_load_ushort v25, v0, s[98:99] offset:-4096
	global_load_ushort v237, v0, s[98:99]
	s_add_u32 s98, s98, 0x2000
	s_addc_u32 s99, s99, 0
	global_load_ushort v26, v0, s[98:99] offset:-4096
	global_load_ushort v238, v0, s[98:99]
	s_add_u32 s98, s98, 0x2000
	s_addc_u32 s99, s99, 0
	global_load_ushort v27, v0, s[98:99] offset:-4096
	global_load_ushort v239, v0, s[98:99]
	s_add_u32 s98, s98, 0x2000
	s_addc_u32 s99, s99, 0
	global_load_ushort v28, v0, s[98:99] offset:-4096
	global_load_ushort v240, v0, s[98:99]
	s_add_u32 s98, s98, 0x2000
	s_addc_u32 s99, s99, 0
	global_load_ushort v29, v0, s[98:99] offset:-4096
	global_load_ushort v241, v0, s[98:99]
	s_add_u32 s98, s98, 0x2000
	s_addc_u32 s99, s99, 0
	global_load_ushort v30, v0, s[98:99] offset:-4096
	global_load_ushort v242, v0, s[98:99]
	s_add_u32 s98, s98, 0x2000
	s_addc_u32 s99, s99, 0
	global_load_ushort v31, v0, s[98:99] offset:-4096
	global_load_ushort v243, v0, s[98:99]
	s_waitcnt vmcnt(28)
	v_lshl_or_b32 v2, v214, 16, v2
	v_lshl_or_b32 v3, v215, 16, v3
	v_lshl_or_b32 v4, v216, 16, v4
	v_lshl_or_b32 v5, v217, 16, v5
	v_lshl_or_b32 v6, v218, 16, v6
	v_lshl_or_b32 v7, v219, 16, v7
	v_lshl_or_b32 v8, v220, 16, v8
	v_lshl_or_b32 v9, v221, 16, v9
	v_lshl_or_b32 v10, v222, 16, v10
	v_lshl_or_b32 v11, v223, 16, v11
	v_lshl_or_b32 v12, v224, 16, v12
	v_lshl_or_b32 v13, v225, 16, v13
	v_lshl_or_b32 v14, v226, 16, v14
	v_lshl_or_b32 v15, v227, 16, v15
	v_lshl_or_b32 v16, v228, 16, v16
	v_lshl_or_b32 v17, v229, 16, v17
	s_add_u32 s98, s98, 0x2000
	s_addc_u32 s99, s99, 0
	global_load_ushort v32, v0, s[98:99] offset:-4096
	global_load_ushort v244, v0, s[98:99]
	s_add_u32 s98, s98, 0x2000
	s_addc_u32 s99, s99, 0
	global_load_ushort v33, v0, s[98:99] offset:-4096
	global_load_ushort v245, v0, s[98:99]
	s_waitcnt vmcnt(0)
	v_lshl_or_b32 v18, v230, 16, v18
	v_lshl_or_b32 v19, v231, 16, v19
	v_lshl_or_b32 v20, v232, 16, v20
	v_lshl_or_b32 v21, v233, 16, v21
	v_lshl_or_b32 v22, v234, 16, v22
	v_lshl_or_b32 v23, v235, 16, v23
	v_lshl_or_b32 v24, v236, 16, v24
	v_lshl_or_b32 v25, v237, 16, v25
	v_lshl_or_b32 v26, v238, 16, v26
	v_lshl_or_b32 v27, v239, 16, v27
	v_lshl_or_b32 v28, v240, 16, v28
	v_lshl_or_b32 v29, v241, 16, v29
	v_lshl_or_b32 v30, v242, 16, v30
	v_lshl_or_b32 v31, v243, 16, v31
	v_lshl_or_b32 v32, v244, 16, v32
	v_lshl_or_b32 v33, v245, 16, v33
	s_branch .LBB0_1510
